# rec_pass1 o_intra stores 4x8B -> 2x16B write-through (permlane16_swap); attention stores unchanged
# baseline (speedup 1.0000x reference)
.LBB0_230:
	s_or_b64 exec, exec, s[2:3]
	v_lshlrev_b64 v[8:9], 10, v[100:101]
	v_lshl_add_u64 v[8:9], s[68:69], 0, v[8:9]
	v_lshlrev_b32_e32 v176, 1, v176
	v_lshl_add_u64 v[8:9], v[8:9], 0, v[176:177]
	v_lshlrev_b32_e32 v176, 1, v24
	v_lshl_add_u64 v[8:9], v[8:9], 0, v[176:177]
	s_mov_b64 s[2:3], 0xdce4200
	v_lshl_add_u64 v[10:11], v[8:9], 0, s[2:3]
	s_mov_b32 s2, 0xdce4000
	v_cvt_pk_bf16_f32 v220, v4, v5
	v_cvt_pk_bf16_f32 v221, v6, v7
	v_cvt_pk_bf16_f32 v222, v0, v1
	v_cvt_pk_bf16_f32 v223, v2, v3
	v_cvt_pk_bf16_f32 v224, v16, v17
	v_cvt_pk_bf16_f32 v225, v18, v19
	v_cvt_pk_bf16_f32 v226, v20, v21
	v_cvt_pk_bf16_f32 v227, v22, v23
	v_and_b32_e32 v228, 4, v24
	v_mul_u32_u24_e32 v228, 6, v228
	v_mov_b32_e32 v229, v177
	v_lshl_add_u64 v[228:229], v[10:11], 0, v[228:229]
	v_permlane16_swap_b32_e32 v220, v222
	v_permlane16_swap_b32_e32 v221, v223
	v_permlane16_swap_b32_e32 v224, v226
	v_permlane16_swap_b32_e32 v225, v227
	s_nop 1
	global_store_dwordx4 v[228:229], v[220:223], off sc1
	global_store_dwordx4 v[228:229], v[224:227], off offset:64 sc1
	s_mov_b64 s[2:3], 0

.LBB0_290:
	s_or_b64 exec, exec, s[2:3]
	v_lshlrev_b64 v[12:13], 10, v[24:25]
	v_lshl_add_u64 v[12:13], s[62:63], 0, v[12:13]
	v_lshl_add_u64 v[12:13], v[12:13], 0, v[176:177]
	v_lshlrev_b32_e32 v176, 1, v30
	v_lshl_add_u64 v[12:13], v[12:13], 0, v[176:177]
	v_cvt_pk_bf16_f32 v70, v0, v1
	v_cvt_pk_bf16_f32 v71, v2, v3
	v_cvt_pk_bf16_f32 v72, v4, v5
	v_cvt_pk_bf16_f32 v73, v6, v7
	v_cvt_pk_bf16_f32 v74, v8, v9
	v_cvt_pk_bf16_f32 v75, v10, v11
	v_cvt_pk_bf16_f32 v76, v20, v21
	v_cvt_pk_bf16_f32 v77, v22, v23
	v_and_b32_e32 v78, 4, v30
	v_mul_u32_u24_e32 v78, 6, v78
	v_mov_b32_e32 v79, v177
	v_lshl_add_u64 v[78:79], v[12:13], 0, v[78:79]
	v_permlane16_swap_b32_e32 v70, v72
	v_permlane16_swap_b32_e32 v71, v73
	v_permlane16_swap_b32_e32 v74, v76
	v_permlane16_swap_b32_e32 v75, v77
	s_nop 1
	global_store_dwordx4 v[78:79], v[70:73], off sc1
	global_store_dwordx4 v[78:79], v[74:77], off offset:64 sc1
